# Strategy 4 variant: static s_setprio 1 for waves 0-3 (earlier half) in GEMM K-loops, no per-phase setprio
# baseline (speedup 1.0000x reference)
; template <class Epi, class Sched, bool ALIGN_EPI = false, bool SP2 = false>
; __device__ __forceinline__ void gemm_phase(PG8_LAS unsigned char* lds, const Gemm g, const Sched& S, const Epi& E, const int tid) {
;     ...
;         const bool has_next = S.next(ui + 1, nxt);
;         const char* nA = has_next ? (const char*)g.A + (size_t)nxt.pm * tstep : cA; const char* nB = has_next ? (const char*)g.Bt + (size_t)nxt.pn * tstep : cB;
;         for (int t = 0; t < nt; t += 2) {
;             const bool last = (t == nt - 2);
;             const char* a1 = cA + (size_t)(t + 1) * kstep;
;             const char* a2 = last ? nA : cA + (size_t)(t + 2) * kstep; const char* b2 = last ? nB : cB + (size_t)(t + 2) * kstep;
;             const char* a3 = a2 + kstep; const char* b3 = b2 + kstep;
;     ...
; #pragma unroll
;         for (int a = 0; a < 2; ++a)
; #pragma unroll
;             for (int b = 0; b < 2; ++b)
; #pragma unroll
;                 for (int m = 0; m < 4; ++m)
; #pragma unroll
;                     for (int n = 0; n < 2; ++n) acc[a][b][m][n] = (f32x4){0.f, 0.f, 0.f, 0.f};
.LBB0_210:
	s_ashr_i32 s49, s48, 31
	s_lshl_b64 s[50:51], s[48:49], 20
	s_add_u32 s50, s2, s50
	s_addc_u32 s51, s36, s51
	s_and_b64 s[52:53], s[40:41], exec
	s_cselect_b32 s49, s51, s57
	s_cselect_b32 s72, s50, s56
	s_ashr_i32 s47, s46, 31
	s_lshl_b64 s[52:53], s[46:47], 20
	s_add_u32 s52, s38, s52
	s_addc_u32 s53, s39, s53
	s_and_b64 s[58:59], s[40:41], exec
	s_cselect_b32 s47, s53, s55
	s_cselect_b32 s73, s52, s54
	s_cselect_b32 s100, 0, 0xf00
	s_add_u32 s72, s72, s100
	s_addc_u32 s49, s49, 0
	s_add_u32 s73, s73, s100
	s_addc_u32 s47, s47, 0
	s_add_u32 s75, s54, 0x100
	s_addc_u32 s76, s55, 0
	s_add_u32 s54, s56, 0x80080
	v_mov_b32_e32 v0, 0
	s_addc_u32 s55, s57, 0
	s_mov_b32 s77, -2
	v_mov_b32_e32 v1, v0
	v_mov_b32_e32 v2, v0
	v_mov_b32_e32 v3, v0
	v_mov_b32_e32 v8, v0
	v_mov_b32_e32 v9, v0
	v_mov_b32_e32 v10, v0
	v_mov_b32_e32 v11, v0
	v_mov_b32_e32 v16, v0
	v_mov_b32_e32 v17, v0
	v_mov_b32_e32 v18, v0
	v_mov_b32_e32 v19, v0
	v_mov_b32_e32 v24, v0
	v_mov_b32_e32 v25, v0
	v_mov_b32_e32 v26, v0
	v_mov_b32_e32 v27, v0
	v_mov_b32_e32 v32, v0
	v_mov_b32_e32 v33, v0
	v_mov_b32_e32 v34, v0
	v_mov_b32_e32 v35, v0
	v_mov_b32_e32 v40, v0
	v_mov_b32_e32 v41, v0
	v_mov_b32_e32 v42, v0
	v_mov_b32_e32 v43, v0
	v_mov_b32_e32 v48, v0
	v_mov_b32_e32 v49, v0
	v_mov_b32_e32 v50, v0
	v_mov_b32_e32 v51, v0
	v_mov_b32_e32 v56, v0
	v_mov_b32_e32 v57, v0
	v_mov_b32_e32 v58, v0
	v_mov_b32_e32 v59, v0
	v_mov_b32_e32 v4, v0
	v_mov_b32_e32 v5, v0
	v_mov_b32_e32 v6, v0
	v_mov_b32_e32 v7, v0
	v_mov_b32_e32 v12, v0
	v_mov_b32_e32 v13, v0
	v_mov_b32_e32 v14, v0
	v_mov_b32_e32 v15, v0
	v_mov_b32_e32 v20, v0
	v_mov_b32_e32 v21, v0
	v_mov_b32_e32 v22, v0
	v_mov_b32_e32 v23, v0
	v_mov_b32_e32 v28, v0
	v_mov_b32_e32 v29, v0
	v_mov_b32_e32 v30, v0
	v_mov_b32_e32 v31, v0
	v_mov_b32_e32 v36, v0
	v_mov_b32_e32 v37, v0
	v_mov_b32_e32 v38, v0
	v_mov_b32_e32 v39, v0
	v_mov_b32_e32 v44, v0
	v_mov_b32_e32 v45, v0
	v_mov_b32_e32 v46, v0
	v_mov_b32_e32 v47, v0
	v_mov_b32_e32 v52, v0
	v_mov_b32_e32 v53, v0
	v_mov_b32_e32 v54, v0
	v_mov_b32_e32 v55, v0
	v_mov_b32_e32 v60, v0
	v_mov_b32_e32 v61, v0
	v_mov_b32_e32 v62, v0
	v_mov_b32_e32 v63, v0
	v_mov_b32_e32 v64, v0
	v_mov_b32_e32 v65, v0
	v_mov_b32_e32 v66, v0
	v_mov_b32_e32 v67, v0
	v_mov_b32_e32 v72, v0
	v_mov_b32_e32 v73, v0
	v_mov_b32_e32 v74, v0
	v_mov_b32_e32 v75, v0
	v_mov_b32_e32 v80, v0
	v_mov_b32_e32 v81, v0
	v_mov_b32_e32 v82, v0
	v_mov_b32_e32 v83, v0
	v_mov_b32_e32 v88, v0
	v_mov_b32_e32 v89, v0
	v_mov_b32_e32 v90, v0
	v_mov_b32_e32 v91, v0
	v_mov_b32_e32 v102, v0
	v_mov_b32_e32 v103, v0
	v_mov_b32_e32 v104, v0
	v_mov_b32_e32 v105, v0
	v_mov_b32_e32 v110, v0
	v_mov_b32_e32 v111, v0
	v_mov_b32_e32 v112, v0
	v_mov_b32_e32 v113, v0
	v_mov_b32_e32 v118, v0
	v_mov_b32_e32 v119, v0
	v_mov_b32_e32 v120, v0
	v_mov_b32_e32 v121, v0
	v_mov_b32_e32 v122, v0
	v_mov_b32_e32 v123, v0
	v_mov_b32_e32 v124, v0
	v_mov_b32_e32 v125, v0
	v_mov_b32_e32 v68, v0
	v_mov_b32_e32 v69, v0
	v_mov_b32_e32 v70, v0
	v_mov_b32_e32 v71, v0
	v_mov_b32_e32 v76, v0
	v_mov_b32_e32 v77, v0
	v_mov_b32_e32 v78, v0
	v_mov_b32_e32 v79, v0
	v_mov_b32_e32 v84, v0
	v_mov_b32_e32 v85, v0
	v_mov_b32_e32 v86, v0
	v_mov_b32_e32 v87, v0
	v_mov_b32_e32 v92, v0
	v_mov_b32_e32 v93, v0
	v_mov_b32_e32 v94, v0
	v_mov_b32_e32 v95, v0
	v_mov_b32_e32 v106, v0
	v_mov_b32_e32 v107, v0
	v_mov_b32_e32 v108, v0
	v_mov_b32_e32 v109, v0
	v_mov_b32_e32 v114, v0
	v_mov_b32_e32 v115, v0
	v_mov_b32_e32 v116, v0
	v_mov_b32_e32 v117, v0
	v_mov_b32_e32 v126, v0
	v_mov_b32_e32 v127, v0
	v_mov_b32_e32 v128, v0
	v_mov_b32_e32 v129, v0
	v_mov_b32_e32 v130, v0
	v_mov_b32_e32 v131, v0
	v_mov_b32_e32 v132, v0
	v_mov_b32_e32 v133, v0
	s_cmp_lt_u32 s81, 0x100
	s_cbranch_scc0 .Lsp_211
	s_setprio 1

; template <class Epi, class Sched, bool ALIGN_EPI = false, bool SP2 = false>
; __device__ __forceinline__ void gemm_phase(PG8_LAS unsigned char* lds, const Gemm g, const Sched& S, const Epi& E, const int tid) {
;     ...
;         for (int t = 0; t < nt; t += 2) {
;             const bool last = (t == nt - 2);
;             const char* a1 = cA + (size_t)(t + 1) * kstep;
;             const char* a2 = last ? nA : cA + (size_t)(t + 2) * kstep; const char* b2 = last ? nB : cB + (size_t)(t + 2) * kstep;
;             const char* a3 = a2 + kstep; const char* b3 = b2 + kstep;
;     ...
; #pragma unroll
;         for (int a = 0; a < 2; ++a)
; #pragma unroll
;             for (int b = 0; b < 2; ++b)
; #pragma unroll
;                 for (int m = 0; m < 4; ++m)
; #pragma unroll
;                     for (int n = 0; n < 2; ++n) acc[a][b][m][n] = (f32x4){0.f, 0.f, 0.f, 0.f};
.LBB0_402:
	s_add_u32 s72, s52, 0x100
	v_mov_b32_e32 v0, 0
	s_addc_u32 s73, s53, 0
	s_mov_b32 s75, -2
	s_waitcnt lgkmcnt(0)
	v_mov_b32_e32 v1, v0
	v_mov_b32_e32 v2, v0
	v_mov_b32_e32 v3, v0
	v_mov_b32_e32 v4, v0
	v_mov_b32_e32 v5, v0
	v_mov_b32_e32 v6, v0
	v_mov_b32_e32 v7, v0
	v_mov_b32_e32 v16, v0
	v_mov_b32_e32 v17, v0
	v_mov_b32_e32 v18, v0
	v_mov_b32_e32 v19, v0
	v_mov_b32_e32 v20, v0
	v_mov_b32_e32 v21, v0
	v_mov_b32_e32 v22, v0
	v_mov_b32_e32 v23, v0
	v_mov_b32_e32 v32, v0
	v_mov_b32_e32 v33, v0
	v_mov_b32_e32 v34, v0
	v_mov_b32_e32 v35, v0
	v_mov_b32_e32 v36, v0
	v_mov_b32_e32 v37, v0
	v_mov_b32_e32 v38, v0
	v_mov_b32_e32 v39, v0
	v_mov_b32_e32 v48, v0
	v_mov_b32_e32 v49, v0
	v_mov_b32_e32 v50, v0
	v_mov_b32_e32 v51, v0
	v_mov_b32_e32 v52, v0
	v_mov_b32_e32 v53, v0
	v_mov_b32_e32 v54, v0
	v_mov_b32_e32 v55, v0
	v_mov_b32_e32 v8, v0
	v_mov_b32_e32 v9, v0
	v_mov_b32_e32 v10, v0
	v_mov_b32_e32 v11, v0
	v_mov_b32_e32 v12, v0
	v_mov_b32_e32 v13, v0
	v_mov_b32_e32 v14, v0
	v_mov_b32_e32 v15, v0
	v_mov_b32_e32 v24, v0
	v_mov_b32_e32 v25, v0
	v_mov_b32_e32 v26, v0
	v_mov_b32_e32 v27, v0
	v_mov_b32_e32 v28, v0
	v_mov_b32_e32 v29, v0
	v_mov_b32_e32 v30, v0
	v_mov_b32_e32 v31, v0
	v_mov_b32_e32 v40, v0
	v_mov_b32_e32 v41, v0
	v_mov_b32_e32 v42, v0
	v_mov_b32_e32 v43, v0
	v_mov_b32_e32 v44, v0
	v_mov_b32_e32 v45, v0
	v_mov_b32_e32 v46, v0
	v_mov_b32_e32 v47, v0
	v_mov_b32_e32 v56, v0
	v_mov_b32_e32 v57, v0
	v_mov_b32_e32 v58, v0
	v_mov_b32_e32 v59, v0
	v_mov_b32_e32 v60, v0
	v_mov_b32_e32 v61, v0
	v_mov_b32_e32 v62, v0
	v_mov_b32_e32 v63, v0
	v_mov_b32_e32 v64, v0
	v_mov_b32_e32 v65, v0
	v_mov_b32_e32 v66, v0
	v_mov_b32_e32 v67, v0
	v_mov_b32_e32 v68, v0
	v_mov_b32_e32 v69, v0
	v_mov_b32_e32 v70, v0
	v_mov_b32_e32 v71, v0
	v_mov_b32_e32 v80, v0
	v_mov_b32_e32 v81, v0
	v_mov_b32_e32 v82, v0
	v_mov_b32_e32 v83, v0
	v_mov_b32_e32 v84, v0
	v_mov_b32_e32 v85, v0
	v_mov_b32_e32 v86, v0
	v_mov_b32_e32 v87, v0
	v_mov_b32_e32 v102, v0
	v_mov_b32_e32 v103, v0
	v_mov_b32_e32 v104, v0
	v_mov_b32_e32 v105, v0
	v_mov_b32_e32 v106, v0
	v_mov_b32_e32 v107, v0
	v_mov_b32_e32 v108, v0
	v_mov_b32_e32 v109, v0
	v_mov_b32_e32 v118, v0
	v_mov_b32_e32 v119, v0
	v_mov_b32_e32 v120, v0
	v_mov_b32_e32 v121, v0
	v_mov_b32_e32 v122, v0
	v_mov_b32_e32 v123, v0
	v_mov_b32_e32 v124, v0
	v_mov_b32_e32 v125, v0
	v_mov_b32_e32 v72, v0
	v_mov_b32_e32 v73, v0
	v_mov_b32_e32 v74, v0
	v_mov_b32_e32 v75, v0
	v_mov_b32_e32 v76, v0
	v_mov_b32_e32 v77, v0
	v_mov_b32_e32 v78, v0
	v_mov_b32_e32 v79, v0
	v_mov_b32_e32 v88, v0
	v_mov_b32_e32 v89, v0
	v_mov_b32_e32 v90, v0
	v_mov_b32_e32 v91, v0
	v_mov_b32_e32 v92, v0
	v_mov_b32_e32 v93, v0
	v_mov_b32_e32 v94, v0
	v_mov_b32_e32 v95, v0
	v_mov_b32_e32 v110, v0
	v_mov_b32_e32 v111, v0
	v_mov_b32_e32 v112, v0
	v_mov_b32_e32 v113, v0
	v_mov_b32_e32 v114, v0
	v_mov_b32_e32 v115, v0
	v_mov_b32_e32 v116, v0
	v_mov_b32_e32 v117, v0
	v_mov_b32_e32 v134, v0
	v_mov_b32_e32 v135, v0
	v_mov_b32_e32 v136, v0
	v_mov_b32_e32 v137, v0
	v_mov_b32_e32 v138, v0
	v_mov_b32_e32 v139, v0
	v_mov_b32_e32 v140, v0
	v_mov_b32_e32 v141, v0
	s_cmp_lt_u32 s81, 0x100
	s_cbranch_scc0 .Lsp_403
	s_setprio 1

; template <class Epi, class Sched, bool ALIGN_EPI = false, bool SP2 = false>
; __device__ __forceinline__ void gemm_phase(PG8_LAS unsigned char* lds, const Gemm g, const Sched& S, const Epi& E, const int tid) {
;     ...
;         const bool has_next = S.next(ui + 1, nxt);
;         const char* nA = has_next ? (const char*)g.A + (size_t)nxt.pm * tstep : cA; const char* nB = has_next ? (const char*)g.Bt + (size_t)nxt.pn * tstep : cB;
;         for (int t = 0; t < nt; t += 2) {
;             const bool last = (t == nt - 2);
;             const char* a1 = cA + (size_t)(t + 1) * kstep;
;             const char* a2 = last ? nA : cA + (size_t)(t + 2) * kstep; const char* b2 = last ? nB : cB + (size_t)(t + 2) * kstep;
;             const char* a3 = a2 + kstep; const char* b3 = b2 + kstep;
;     ...
; #pragma unroll
;         for (int a = 0; a < 2; ++a)
; #pragma unroll
;             for (int b = 0; b < 2; ++b)
; #pragma unroll
;                 for (int m = 0; m < 4; ++m)
; #pragma unroll
;                     for (int n = 0; n < 2; ++n) acc[a][b][m][n] = (f32x4){0.f, 0.f, 0.f, 0.f};
.LBB0_487:
	s_ashr_i32 s53, s52, 31
	s_lshl_b64 s[54:55], s[52:53], 20
	s_add_u32 s54, s2, s54
	s_addc_u32 s55, s36, s55
	s_and_b64 s[56:57], s[40:41], exec
	s_cselect_b32 s53, s55, s59
	s_cselect_b32 s72, s54, s58
	s_ashr_i32 s51, s50, 31
	s_lshl_b64 s[56:57], s[50:51], 20
	s_add_u32 s56, s38, s56
	s_addc_u32 s57, s39, s57
	s_and_b64 s[60:61], s[40:41], exec
	s_cselect_b32 s51, s57, s43
	s_cselect_b32 s73, s56, s42
	s_cselect_b32 s100, 0, 0xf00
	s_add_u32 s72, s72, s100
	s_addc_u32 s53, s53, 0
	s_add_u32 s73, s73, s100
	s_addc_u32 s51, s51, 0
	s_add_u32 s75, s42, 0x100
	s_addc_u32 s76, s43, 0
	s_add_u32 s42, s58, 0x80080
	v_mov_b32_e32 v0, 0
	s_addc_u32 s43, s59, 0
	s_mov_b32 s77, -2
	v_mov_b32_e32 v1, v0
	v_mov_b32_e32 v2, v0
	v_mov_b32_e32 v3, v0
	v_mov_b32_e32 v12, v0
	v_mov_b32_e32 v13, v0
	v_mov_b32_e32 v14, v0
	v_mov_b32_e32 v15, v0
	v_mov_b32_e32 v16, v0
	v_mov_b32_e32 v17, v0
	v_mov_b32_e32 v18, v0
	v_mov_b32_e32 v19, v0
	v_mov_b32_e32 v28, v0
	v_mov_b32_e32 v29, v0
	v_mov_b32_e32 v30, v0
	v_mov_b32_e32 v31, v0
	v_mov_b32_e32 v32, v0
	v_mov_b32_e32 v33, v0
	v_mov_b32_e32 v34, v0
	v_mov_b32_e32 v35, v0
	v_mov_b32_e32 v44, v0
	v_mov_b32_e32 v45, v0
	v_mov_b32_e32 v46, v0
	v_mov_b32_e32 v47, v0
	v_mov_b32_e32 v48, v0
	v_mov_b32_e32 v49, v0
	v_mov_b32_e32 v50, v0
	v_mov_b32_e32 v51, v0
	v_mov_b32_e32 v60, v0
	v_mov_b32_e32 v61, v0
	v_mov_b32_e32 v62, v0
	v_mov_b32_e32 v63, v0
	v_mov_b32_e32 v4, v0
	v_mov_b32_e32 v5, v0
	v_mov_b32_e32 v6, v0
	v_mov_b32_e32 v7, v0
	v_mov_b32_e32 v8, v0
	v_mov_b32_e32 v9, v0
	v_mov_b32_e32 v10, v0
	v_mov_b32_e32 v11, v0
	v_mov_b32_e32 v20, v0
	v_mov_b32_e32 v21, v0
	v_mov_b32_e32 v22, v0
	v_mov_b32_e32 v23, v0
	v_mov_b32_e32 v24, v0
	v_mov_b32_e32 v25, v0
	v_mov_b32_e32 v26, v0
	v_mov_b32_e32 v27, v0
	v_mov_b32_e32 v36, v0
	v_mov_b32_e32 v37, v0
	v_mov_b32_e32 v38, v0
	v_mov_b32_e32 v39, v0
	v_mov_b32_e32 v40, v0
	v_mov_b32_e32 v41, v0
	v_mov_b32_e32 v42, v0
	v_mov_b32_e32 v43, v0
	v_mov_b32_e32 v52, v0
	v_mov_b32_e32 v53, v0
	v_mov_b32_e32 v54, v0
	v_mov_b32_e32 v55, v0
	v_mov_b32_e32 v56, v0
	v_mov_b32_e32 v57, v0
	v_mov_b32_e32 v58, v0
	v_mov_b32_e32 v59, v0
	v_mov_b32_e32 v64, v0
	v_mov_b32_e32 v65, v0
	v_mov_b32_e32 v66, v0
	v_mov_b32_e32 v67, v0
	v_mov_b32_e32 v76, v0
	v_mov_b32_e32 v77, v0
	v_mov_b32_e32 v78, v0
	v_mov_b32_e32 v79, v0
	v_mov_b32_e32 v80, v0
	v_mov_b32_e32 v81, v0
	v_mov_b32_e32 v82, v0
	v_mov_b32_e32 v83, v0
	v_mov_b32_e32 v92, v0
	v_mov_b32_e32 v93, v0
	v_mov_b32_e32 v94, v0
	v_mov_b32_e32 v95, v0
	v_mov_b32_e32 v102, v0
	v_mov_b32_e32 v103, v0
	v_mov_b32_e32 v104, v0
	v_mov_b32_e32 v105, v0
	v_mov_b32_e32 v114, v0
	v_mov_b32_e32 v115, v0
	v_mov_b32_e32 v116, v0
	v_mov_b32_e32 v117, v0
	v_mov_b32_e32 v126, v0
	v_mov_b32_e32 v127, v0
	v_mov_b32_e32 v128, v0
	v_mov_b32_e32 v129, v0
	v_mov_b32_e32 v130, v0
	v_mov_b32_e32 v131, v0
	v_mov_b32_e32 v132, v0
	v_mov_b32_e32 v133, v0
	v_mov_b32_e32 v68, v0
	v_mov_b32_e32 v69, v0
	v_mov_b32_e32 v70, v0
	v_mov_b32_e32 v71, v0
	v_mov_b32_e32 v72, v0
	v_mov_b32_e32 v73, v0
	v_mov_b32_e32 v74, v0
	v_mov_b32_e32 v75, v0
	v_mov_b32_e32 v84, v0
	v_mov_b32_e32 v85, v0
	v_mov_b32_e32 v86, v0
	v_mov_b32_e32 v87, v0
	v_mov_b32_e32 v88, v0
	v_mov_b32_e32 v89, v0
	v_mov_b32_e32 v90, v0
	v_mov_b32_e32 v91, v0
	v_mov_b32_e32 v106, v0
	v_mov_b32_e32 v107, v0
	v_mov_b32_e32 v108, v0
	v_mov_b32_e32 v109, v0
	v_mov_b32_e32 v110, v0
	v_mov_b32_e32 v111, v0
	v_mov_b32_e32 v112, v0
	v_mov_b32_e32 v113, v0
	v_mov_b32_e32 v118, v0
	v_mov_b32_e32 v119, v0
	v_mov_b32_e32 v120, v0
	v_mov_b32_e32 v121, v0
	v_mov_b32_e32 v122, v0
	v_mov_b32_e32 v123, v0
	v_mov_b32_e32 v124, v0
	v_mov_b32_e32 v125, v0
	s_cmp_lt_u32 s81, 0x100
	s_cbranch_scc0 .Lsp_488
	s_setprio 1

; template <class Epi, class Sched, bool ALIGN_EPI = false, bool SP2 = false>
; __device__ __forceinline__ void gemm_phase(PG8_LAS unsigned char* lds, const Gemm g, const Sched& S, const Epi& E, const int tid) {
;     ...
;         const bool has_next = S.next(ui + 1, nxt);
;         const char* nA = has_next ? (const char*)g.A + (size_t)nxt.pm * tstep : cA; const char* nB = has_next ? (const char*)g.Bt + (size_t)nxt.pn * tstep : cB;
;         for (int t = 0; t < nt; t += 2) {
;             const bool last = (t == nt - 2);
;             const char* a1 = cA + (size_t)(t + 1) * kstep;
;             const char* a2 = last ? nA : cA + (size_t)(t + 2) * kstep; const char* b2 = last ? nB : cB + (size_t)(t + 2) * kstep;
;             const char* a3 = a2 + kstep; const char* b3 = b2 + kstep;
;     ...
; #pragma unroll
;         for (int a = 0; a < 2; ++a)
; #pragma unroll
;             for (int b = 0; b < 2; ++b)
; #pragma unroll
;                 for (int m = 0; m < 4; ++m)
; #pragma unroll
;                     for (int n = 0; n < 2; ++n) acc[a][b][m][n] = (f32x4){0.f, 0.f, 0.f, 0.f};
.LBB0_1198:
	s_ashr_i32 s49, s48, 31
	v_cmp_lt_i64_e32 vcc, s[50:51], v[244:245]
	s_lshl_b64 s[50:51], s[48:49], 20
	s_add_u32 s50, s36, s50
	s_addc_u32 s51, s38, s51
	s_and_b64 s[52:53], vcc, exec
	s_cselect_b32 s49, s51, s57
	s_cselect_b32 s71, s50, s56
	s_ashr_i32 s47, s46, 31
	s_lshl_b64 s[52:53], s[46:47], 20
	s_add_u32 s52, s39, s52
	s_addc_u32 s53, s60, s53
	s_and_b64 s[58:59], vcc, exec
	s_cselect_b32 s47, s53, s55
	s_cselect_b32 s72, s52, s54
	s_cselect_b32 s100, 0, 0xf00
	s_add_u32 s71, s71, s100
	s_addc_u32 s49, s49, 0
	s_add_u32 s72, s72, s100
	s_addc_u32 s47, s47, 0
	s_add_u32 s73, s54, 0x100
	s_addc_u32 s75, s55, 0
	s_add_u32 s54, s56, 0x80080
	v_mov_b32_e32 v0, 0
	s_addc_u32 s55, s57, 0
	s_mov_b32 s76, -2
	s_waitcnt lgkmcnt(0)
	v_mov_b32_e32 v1, v0
	v_mov_b32_e32 v2, v0
	v_mov_b32_e32 v3, v0
	v_mov_b32_e32 v4, v0
	v_mov_b32_e32 v5, v0
	v_mov_b32_e32 v6, v0
	v_mov_b32_e32 v7, v0
	v_mov_b32_e32 v16, v0
	v_mov_b32_e32 v17, v0
	v_mov_b32_e32 v18, v0
	v_mov_b32_e32 v19, v0
	v_mov_b32_e32 v20, v0
	v_mov_b32_e32 v21, v0
	v_mov_b32_e32 v22, v0
	v_mov_b32_e32 v23, v0
	v_mov_b32_e32 v32, v0
	v_mov_b32_e32 v33, v0
	v_mov_b32_e32 v34, v0
	v_mov_b32_e32 v35, v0
	v_mov_b32_e32 v36, v0
	v_mov_b32_e32 v37, v0
	v_mov_b32_e32 v38, v0
	v_mov_b32_e32 v39, v0
	v_mov_b32_e32 v48, v0
	v_mov_b32_e32 v49, v0
	v_mov_b32_e32 v50, v0
	v_mov_b32_e32 v51, v0
	v_mov_b32_e32 v52, v0
	v_mov_b32_e32 v53, v0
	v_mov_b32_e32 v54, v0
	v_mov_b32_e32 v55, v0
	v_mov_b32_e32 v8, v0
	v_mov_b32_e32 v9, v0
	v_mov_b32_e32 v10, v0
	v_mov_b32_e32 v11, v0
	v_mov_b32_e32 v12, v0
	v_mov_b32_e32 v13, v0
	v_mov_b32_e32 v14, v0
	v_mov_b32_e32 v15, v0
	v_mov_b32_e32 v24, v0
	v_mov_b32_e32 v25, v0
	v_mov_b32_e32 v26, v0
	v_mov_b32_e32 v27, v0
	v_mov_b32_e32 v28, v0
	v_mov_b32_e32 v29, v0
	v_mov_b32_e32 v30, v0
	v_mov_b32_e32 v31, v0
	v_mov_b32_e32 v40, v0
	v_mov_b32_e32 v41, v0
	v_mov_b32_e32 v42, v0
	v_mov_b32_e32 v43, v0
	v_mov_b32_e32 v44, v0
	v_mov_b32_e32 v45, v0
	v_mov_b32_e32 v46, v0
	v_mov_b32_e32 v47, v0
	v_mov_b32_e32 v56, v0
	v_mov_b32_e32 v57, v0
	v_mov_b32_e32 v58, v0
	v_mov_b32_e32 v59, v0
	v_mov_b32_e32 v60, v0
	v_mov_b32_e32 v61, v0
	v_mov_b32_e32 v62, v0
	v_mov_b32_e32 v63, v0
	v_mov_b32_e32 v64, v0
	v_mov_b32_e32 v65, v0
	v_mov_b32_e32 v66, v0
	v_mov_b32_e32 v67, v0
	v_mov_b32_e32 v68, v0
	v_mov_b32_e32 v69, v0
	v_mov_b32_e32 v70, v0
	v_mov_b32_e32 v71, v0
	v_mov_b32_e32 v80, v0
	v_mov_b32_e32 v81, v0
	v_mov_b32_e32 v82, v0
	v_mov_b32_e32 v83, v0
	v_mov_b32_e32 v84, v0
	v_mov_b32_e32 v85, v0
	v_mov_b32_e32 v86, v0
	v_mov_b32_e32 v87, v0
	v_mov_b32_e32 v102, v0
	v_mov_b32_e32 v103, v0
	v_mov_b32_e32 v104, v0
	v_mov_b32_e32 v105, v0
	v_mov_b32_e32 v106, v0
	v_mov_b32_e32 v107, v0
	v_mov_b32_e32 v108, v0
	v_mov_b32_e32 v109, v0
	v_mov_b32_e32 v118, v0
	v_mov_b32_e32 v119, v0
	v_mov_b32_e32 v120, v0
	v_mov_b32_e32 v121, v0
	v_mov_b32_e32 v122, v0
	v_mov_b32_e32 v123, v0
	v_mov_b32_e32 v124, v0
	v_mov_b32_e32 v125, v0
	v_mov_b32_e32 v72, v0
	v_mov_b32_e32 v73, v0
	v_mov_b32_e32 v74, v0
	v_mov_b32_e32 v75, v0
	v_mov_b32_e32 v76, v0
	v_mov_b32_e32 v77, v0
	v_mov_b32_e32 v78, v0
	v_mov_b32_e32 v79, v0
	v_mov_b32_e32 v88, v0
	v_mov_b32_e32 v89, v0
	v_mov_b32_e32 v90, v0
	v_mov_b32_e32 v91, v0
	v_mov_b32_e32 v92, v0
	v_mov_b32_e32 v93, v0
	v_mov_b32_e32 v94, v0
	v_mov_b32_e32 v95, v0
	v_mov_b32_e32 v110, v0
	v_mov_b32_e32 v111, v0
	v_mov_b32_e32 v112, v0
	v_mov_b32_e32 v113, v0
	v_mov_b32_e32 v114, v0
	v_mov_b32_e32 v115, v0
	v_mov_b32_e32 v116, v0
	v_mov_b32_e32 v117, v0
	v_mov_b32_e32 v134, v0
	v_mov_b32_e32 v135, v0
	v_mov_b32_e32 v136, v0
	v_mov_b32_e32 v137, v0
	v_mov_b32_e32 v138, v0
	v_mov_b32_e32 v139, v0
	v_mov_b32_e32 v140, v0
	v_mov_b32_e32 v141, v0
	s_cmp_lt_u32 s81, 0x100
	s_cbranch_scc0 .Lsp_1199
	s_setprio 1
